# phase 0 weight conversion: the 32 (+32 gain) loads of every 64x32 weight tile are issued together instead of one dependent round trip per element
# speedup vs baseline: 1.0225x; 1.0109x over previous
.LBB0_12:
	v_cmp_lt_i32_e32 vcc, s33, v54
	s_and_saveexec_b64 s[2:3], vcc
	s_xor_b64 s[12:13], exec, s[2:3]
	s_cbranch_execz .LBB0_62
	v_bfe_u32 v2, v42, 6, 2
	v_lshlrev_b32_e32 v14, 6, v2
	v_or_b32_e32 v28, v32, v14
	v_or_b32_e32 v11, v41, v14
	v_lshl_or_b32 v12, v2, 8, v8
	v_mov_b32_e32 v13, v1
	v_or_b32_e32 v16, v43, v14
	v_or_b32_e32 v18, v44, v14
	v_or_b32_e32 v20, v46, v14
	v_or_b32_e32 v22, v47, v14
	v_or_b32_e32 v24, v48, v14
	v_or_b32_e32 v26, v49, v14
	v_lshlrev_b32_e32 v2, 2, v28
	v_cmp_lt_u32_e32 vcc, s34, v54
	s_and_saveexec_b64 s[2:3], vcc
	s_xor_b64 s[14:15], exec, s[2:3]
	s_cbranch_execz .LBB0_41
	v_and_or_b32 v14, v40, s35, v9
	v_mov_b32_e32 v15, v3
	v_lshlrev_b64 v[30:31], 2, v[14:15]
	v_lshlrev_b32_e32 v14, 12, v11
	v_readlane_b32 s60, v247, 0
	v_lshlrev_b32_e32 v16, 12, v16
	v_mov_b32_e32 v17, v3
	v_lshlrev_b32_e32 v18, 12, v18
	v_mov_b32_e32 v19, v3
	v_lshlrev_b32_e32 v20, 12, v20
	v_mov_b32_e32 v21, v3
	v_lshlrev_b32_e32 v22, 12, v22
	v_mov_b32_e32 v23, v3
	v_lshlrev_b32_e32 v24, 12, v24
	v_mov_b32_e32 v25, v3
	v_lshlrev_b32_e32 v26, 12, v26
	v_mov_b32_e32 v27, v3
	v_lshlrev_b32_e32 v28, 12, v28
	v_mov_b32_e32 v29, v3
	v_lshl_add_u64 v[14:15], v[30:31], 0, v[14:15]
	v_readlane_b32 s61, v247, 1
	v_lshl_add_u64 v[16:17], v[30:31], 0, v[16:17]
	v_lshl_add_u64 v[18:19], v[30:31], 0, v[18:19]
	v_lshl_add_u64 v[20:21], v[30:31], 0, v[20:21]
	v_lshl_add_u64 v[22:23], v[30:31], 0, v[22:23]
	v_lshl_add_u64 v[24:25], v[30:31], 0, v[24:25]
	v_lshl_add_u64 v[26:27], v[30:31], 0, v[26:27]
	v_lshl_add_u64 v[28:29], v[28:29], 0, v[30:31]
	v_lshl_add_u64 v[14:15], s[60:61], 0, v[14:15]
	v_lshl_add_u64 v[16:17], s[60:61], 0, v[16:17]
	v_lshl_add_u64 v[18:19], s[60:61], 0, v[18:19]
	v_lshl_add_u64 v[20:21], s[60:61], 0, v[20:21]
	v_lshl_add_u64 v[22:23], s[60:61], 0, v[22:23]
	v_lshl_add_u64 v[24:25], s[60:61], 0, v[24:25]
	v_lshl_add_u64 v[26:27], s[60:61], 0, v[26:27]
	v_lshl_add_u64 v[28:29], s[60:61], 0, v[28:29]
	s_mov_b64 s[24:25], 0
	s_mov_b64 s[26:27], s[48:49]
	v_mov_b32_e32 v30, v39
	v_readlane_b32 s62, v247, 2
	v_readlane_b32 s63, v247, 3
	v_readlane_b32 s64, v247, 4
	v_readlane_b32 s65, v247, 5
	v_readlane_b32 s66, v247, 6
	v_readlane_b32 s67, v247, 7
	v_add_u32_e32 v244, -14, v11
	v_subrev_u32_e32 v245, s60, v28
	v_lshlrev_b32_e32 v243, 12, v244
	v_sub_u32_e32 v245, v245, v243
	s_add_i32 s24, s52, -1
	v_add_u32_e32 v242, 0, v244
	v_min_u32_e32 v242, s24, v242
	v_lshl_add_u32 v112, v242, 12, v245
	global_load_dword v210, v112, s[60:61]
	v_add_u32_e32 v242, 2, v244
	v_min_u32_e32 v242, s24, v242
	v_lshl_add_u32 v243, v242, 12, v245
	global_load_dword v211, v243, s[60:61]
	v_add_u32_e32 v242, 4, v244
	v_min_u32_e32 v242, s24, v242
	v_lshl_add_u32 v112, v242, 12, v245
	global_load_dword v212, v112, s[60:61]
	v_add_u32_e32 v242, 6, v244
	v_min_u32_e32 v242, s24, v242
	v_lshl_add_u32 v243, v242, 12, v245
	global_load_dword v213, v243, s[60:61]
	v_add_u32_e32 v242, 8, v244
	v_min_u32_e32 v242, s24, v242
	v_lshl_add_u32 v112, v242, 12, v245
	global_load_dword v214, v112, s[60:61]
	v_add_u32_e32 v242, 10, v244
	v_min_u32_e32 v242, s24, v242
	v_lshl_add_u32 v243, v242, 12, v245
	global_load_dword v215, v243, s[60:61]
	v_add_u32_e32 v242, 12, v244
	v_min_u32_e32 v242, s24, v242
	v_lshl_add_u32 v112, v242, 12, v245
	global_load_dword v216, v112, s[60:61]
	v_add_u32_e32 v242, 14, v244
	v_min_u32_e32 v242, s24, v242
	v_lshl_add_u32 v243, v242, 12, v245
	global_load_dword v217, v243, s[60:61]
	v_add_u32_e32 v242, 16, v244
	v_min_u32_e32 v242, s24, v242
	v_lshl_add_u32 v112, v242, 12, v245
	global_load_dword v218, v112, s[60:61]
	v_add_u32_e32 v242, 18, v244
	v_min_u32_e32 v242, s24, v242
	v_lshl_add_u32 v243, v242, 12, v245
	global_load_dword v219, v243, s[60:61]
	v_add_u32_e32 v242, 20, v244
	v_min_u32_e32 v242, s24, v242
	v_lshl_add_u32 v112, v242, 12, v245
	global_load_dword v220, v112, s[60:61]
	v_add_u32_e32 v242, 22, v244
	v_min_u32_e32 v242, s24, v242
	v_lshl_add_u32 v243, v242, 12, v245
	global_load_dword v221, v243, s[60:61]
	v_add_u32_e32 v242, 24, v244
	v_min_u32_e32 v242, s24, v242
	v_lshl_add_u32 v112, v242, 12, v245
	global_load_dword v222, v112, s[60:61]
	v_add_u32_e32 v242, 26, v244
	v_min_u32_e32 v242, s24, v242
	v_lshl_add_u32 v243, v242, 12, v245
	global_load_dword v223, v243, s[60:61]
	v_add_u32_e32 v242, 28, v244
	v_min_u32_e32 v242, s24, v242
	v_lshl_add_u32 v112, v242, 12, v245
	global_load_dword v224, v112, s[60:61]
	v_add_u32_e32 v242, 30, v244
	v_min_u32_e32 v242, s24, v242
	v_lshl_add_u32 v243, v242, 12, v245
	global_load_dword v225, v243, s[60:61]
	v_add_u32_e32 v242, 32, v244
	v_min_u32_e32 v242, s24, v242
	v_lshl_add_u32 v112, v242, 12, v245
	global_load_dword v226, v112, s[60:61]
	v_add_u32_e32 v242, 34, v244
	v_min_u32_e32 v242, s24, v242
	v_lshl_add_u32 v243, v242, 12, v245
	global_load_dword v227, v243, s[60:61]
	v_add_u32_e32 v242, 36, v244
	v_min_u32_e32 v242, s24, v242
	v_lshl_add_u32 v112, v242, 12, v245
	global_load_dword v228, v112, s[60:61]
	v_add_u32_e32 v242, 38, v244
	v_min_u32_e32 v242, s24, v242
	v_lshl_add_u32 v243, v242, 12, v245
	global_load_dword v229, v243, s[60:61]
	v_add_u32_e32 v242, 40, v244
	v_min_u32_e32 v242, s24, v242
	v_lshl_add_u32 v112, v242, 12, v245
	global_load_dword v230, v112, s[60:61]
	v_add_u32_e32 v242, 42, v244
	v_min_u32_e32 v242, s24, v242
	v_lshl_add_u32 v243, v242, 12, v245
	global_load_dword v231, v243, s[60:61]
	v_add_u32_e32 v242, 44, v244
	v_min_u32_e32 v242, s24, v242
	v_lshl_add_u32 v112, v242, 12, v245
	global_load_dword v232, v112, s[60:61]
	v_add_u32_e32 v242, 46, v244
	v_min_u32_e32 v242, s24, v242
	v_lshl_add_u32 v243, v242, 12, v245
	global_load_dword v233, v243, s[60:61]
	v_add_u32_e32 v242, 48, v244
	v_min_u32_e32 v242, s24, v242
	v_lshl_add_u32 v112, v242, 12, v245
	global_load_dword v234, v112, s[60:61]
	v_add_u32_e32 v242, 50, v244
	v_min_u32_e32 v242, s24, v242
	v_lshl_add_u32 v243, v242, 12, v245
	global_load_dword v235, v243, s[60:61]
	v_add_u32_e32 v242, 52, v244
	v_min_u32_e32 v242, s24, v242
	v_lshl_add_u32 v112, v242, 12, v245
	global_load_dword v236, v112, s[60:61]
	v_add_u32_e32 v242, 54, v244
	v_min_u32_e32 v242, s24, v242
	v_lshl_add_u32 v243, v242, 12, v245
	global_load_dword v237, v243, s[60:61]
	v_add_u32_e32 v242, 56, v244
	v_min_u32_e32 v242, s24, v242
	v_lshl_add_u32 v112, v242, 12, v245
	global_load_dword v238, v112, s[60:61]
	v_add_u32_e32 v242, 58, v244
	v_min_u32_e32 v242, s24, v242
	v_lshl_add_u32 v243, v242, 12, v245
	global_load_dword v239, v243, s[60:61]
	v_add_u32_e32 v242, 60, v244
	v_min_u32_e32 v242, s24, v242
	v_lshl_add_u32 v112, v242, 12, v245
	global_load_dword v240, v112, s[60:61]
	v_add_u32_e32 v242, 62, v244
	v_min_u32_e32 v242, s24, v242
	v_lshl_add_u32 v243, v242, 12, v245
	global_load_dword v241, v243, s[60:61]
	s_and_b64 vcc, exec, s[8:9]
	s_cbranch_vccz .Lwj3_nogain
	v_add_u32_e32 v242, 0, v244
	v_min_u32_e32 v242, s24, v242
	v_lshlrev_b32_e32 v112, 2, v242
	global_load_dword v192, v112, s[48:49]
	v_add_u32_e32 v242, 2, v244
	v_min_u32_e32 v242, s24, v242
	v_lshlrev_b32_e32 v243, 2, v242
	global_load_dword v193, v243, s[48:49]
	v_add_u32_e32 v242, 4, v244
	v_min_u32_e32 v242, s24, v242
	v_lshlrev_b32_e32 v112, 2, v242
	global_load_dword v194, v112, s[48:49]
	v_add_u32_e32 v242, 6, v244
	v_min_u32_e32 v242, s24, v242
	v_lshlrev_b32_e32 v243, 2, v242
	global_load_dword v195, v243, s[48:49]
	v_add_u32_e32 v242, 8, v244
	v_min_u32_e32 v242, s24, v242
	v_lshlrev_b32_e32 v112, 2, v242
	global_load_dword v196, v112, s[48:49]
	v_add_u32_e32 v242, 10, v244
	v_min_u32_e32 v242, s24, v242
	v_lshlrev_b32_e32 v243, 2, v242
	global_load_dword v197, v243, s[48:49]
	v_add_u32_e32 v242, 12, v244
	v_min_u32_e32 v242, s24, v242
	v_lshlrev_b32_e32 v112, 2, v242
	global_load_dword v198, v112, s[48:49]
	v_add_u32_e32 v242, 14, v244
	v_min_u32_e32 v242, s24, v242
	v_lshlrev_b32_e32 v243, 2, v242
	global_load_dword v199, v243, s[48:49]
	v_add_u32_e32 v242, 16, v244
	v_min_u32_e32 v242, s24, v242
	v_lshlrev_b32_e32 v112, 2, v242
	global_load_dword v200, v112, s[48:49]
	v_add_u32_e32 v242, 18, v244
	v_min_u32_e32 v242, s24, v242
	v_lshlrev_b32_e32 v243, 2, v242
	global_load_dword v201, v243, s[48:49]
	v_add_u32_e32 v242, 20, v244
	v_min_u32_e32 v242, s24, v242
	v_lshlrev_b32_e32 v112, 2, v242
	global_load_dword v202, v112, s[48:49]
	v_add_u32_e32 v242, 22, v244
	v_min_u32_e32 v242, s24, v242
	v_lshlrev_b32_e32 v243, 2, v242
	global_load_dword v203, v243, s[48:49]
	v_add_u32_e32 v242, 24, v244
	v_min_u32_e32 v242, s24, v242
	v_lshlrev_b32_e32 v112, 2, v242
	global_load_dword v204, v112, s[48:49]
	v_add_u32_e32 v242, 26, v244
	v_min_u32_e32 v242, s24, v242
	v_lshlrev_b32_e32 v243, 2, v242
	global_load_dword v205, v243, s[48:49]
	v_add_u32_e32 v242, 28, v244
	v_min_u32_e32 v242, s24, v242
	v_lshlrev_b32_e32 v112, 2, v242
	global_load_dword v206, v112, s[48:49]
	v_add_u32_e32 v242, 30, v244
	v_min_u32_e32 v242, s24, v242
	v_lshlrev_b32_e32 v243, 2, v242
	global_load_dword v207, v243, s[48:49]
	v_add_u32_e32 v242, 32, v244
	v_min_u32_e32 v242, s24, v242
	v_lshlrev_b32_e32 v112, 2, v242
	global_load_dword v144, v112, s[48:49]
	v_add_u32_e32 v242, 34, v244
	v_min_u32_e32 v242, s24, v242
	v_lshlrev_b32_e32 v243, 2, v242
	global_load_dword v145, v243, s[48:49]
	v_add_u32_e32 v242, 36, v244
	v_min_u32_e32 v242, s24, v242
	v_lshlrev_b32_e32 v112, 2, v242
	global_load_dword v146, v112, s[48:49]
	v_add_u32_e32 v242, 38, v244
	v_min_u32_e32 v242, s24, v242
	v_lshlrev_b32_e32 v243, 2, v242
	global_load_dword v147, v243, s[48:49]
	v_add_u32_e32 v242, 40, v244
	v_min_u32_e32 v242, s24, v242
	v_lshlrev_b32_e32 v112, 2, v242
	global_load_dword v148, v112, s[48:49]
	v_add_u32_e32 v242, 42, v244
	v_min_u32_e32 v242, s24, v242
	v_lshlrev_b32_e32 v243, 2, v242
	global_load_dword v149, v243, s[48:49]
	v_add_u32_e32 v242, 44, v244
	v_min_u32_e32 v242, s24, v242
	v_lshlrev_b32_e32 v112, 2, v242
	global_load_dword v150, v112, s[48:49]
	v_add_u32_e32 v242, 46, v244
	v_min_u32_e32 v242, s24, v242
	v_lshlrev_b32_e32 v243, 2, v242
	global_load_dword v151, v243, s[48:49]
	v_add_u32_e32 v242, 48, v244
	v_min_u32_e32 v242, s24, v242
	v_lshlrev_b32_e32 v112, 2, v242
	global_load_dword v152, v112, s[48:49]
	v_add_u32_e32 v242, 50, v244
	v_min_u32_e32 v242, s24, v242
	v_lshlrev_b32_e32 v243, 2, v242
	global_load_dword v153, v243, s[48:49]
	v_add_u32_e32 v242, 52, v244
	v_min_u32_e32 v242, s24, v242
	v_lshlrev_b32_e32 v112, 2, v242
	global_load_dword v154, v112, s[48:49]
	v_add_u32_e32 v242, 54, v244
	v_min_u32_e32 v242, s24, v242
	v_lshlrev_b32_e32 v243, 2, v242
	global_load_dword v155, v243, s[48:49]
	v_add_u32_e32 v242, 56, v244
	v_min_u32_e32 v242, s24, v242
	v_lshlrev_b32_e32 v112, 2, v242
	global_load_dword v156, v112, s[48:49]
	v_add_u32_e32 v242, 58, v244
	v_min_u32_e32 v242, s24, v242
	v_lshlrev_b32_e32 v243, 2, v242
	global_load_dword v157, v243, s[48:49]
	v_add_u32_e32 v242, 60, v244
	v_min_u32_e32 v242, s24, v242
	v_lshlrev_b32_e32 v112, 2, v242
	global_load_dword v158, v112, s[48:49]
	v_add_u32_e32 v242, 62, v244
	v_min_u32_e32 v242, s24, v242
	v_lshlrev_b32_e32 v243, 2, v242
	global_load_dword v159, v243, s[48:49]
	s_waitcnt vmcnt(0)
	v_mul_f32_e32 v210, v210, v192
	v_mul_f32_e32 v211, v211, v193
	v_mul_f32_e32 v212, v212, v194
	v_mul_f32_e32 v213, v213, v195
	v_mul_f32_e32 v214, v214, v196
	v_mul_f32_e32 v215, v215, v197
	v_mul_f32_e32 v216, v216, v198
	v_mul_f32_e32 v217, v217, v199
	v_mul_f32_e32 v218, v218, v200
	v_mul_f32_e32 v219, v219, v201
	v_mul_f32_e32 v220, v220, v202
	v_mul_f32_e32 v221, v221, v203
	v_mul_f32_e32 v222, v222, v204
	v_mul_f32_e32 v223, v223, v205
	v_mul_f32_e32 v224, v224, v206
	v_mul_f32_e32 v225, v225, v207
	v_mul_f32_e32 v226, v226, v144
	v_mul_f32_e32 v227, v227, v145
	v_mul_f32_e32 v228, v228, v146
	v_mul_f32_e32 v229, v229, v147
	v_mul_f32_e32 v230, v230, v148
	v_mul_f32_e32 v231, v231, v149
	v_mul_f32_e32 v232, v232, v150
	v_mul_f32_e32 v233, v233, v151
	v_mul_f32_e32 v234, v234, v152
	v_mul_f32_e32 v235, v235, v153
	v_mul_f32_e32 v236, v236, v154
	v_mul_f32_e32 v237, v237, v155
	v_mul_f32_e32 v238, v238, v156
	v_mul_f32_e32 v239, v239, v157
	v_mul_f32_e32 v240, v240, v158
	v_mul_f32_e32 v241, v241, v159
.Lwj3_nogain:
	s_waitcnt vmcnt(0)
	v_add_u32_e32 v242, 0, v244
	v_cmp_gt_u32_e32 vcc, s52, v242
	s_nop 1
	v_cndmask_b32_e32 v210, 0, v210, vcc
	ds_write_b32 v39, v210
	v_add_u32_e32 v242, 2, v244
	v_cmp_gt_u32_e32 vcc, s52, v242
	s_nop 1
	v_cndmask_b32_e32 v211, 0, v211, vcc
	ds_write_b32 v39, v211 offset:264
	v_add_u32_e32 v242, 4, v244
	v_cmp_gt_u32_e32 vcc, s52, v242
	s_nop 1
	v_cndmask_b32_e32 v212, 0, v212, vcc
	ds_write_b32 v39, v212 offset:528
	v_add_u32_e32 v242, 6, v244
	v_cmp_gt_u32_e32 vcc, s52, v242
	s_nop 1
	v_cndmask_b32_e32 v213, 0, v213, vcc
	ds_write_b32 v39, v213 offset:792
	v_add_u32_e32 v242, 8, v244
	v_cmp_gt_u32_e32 vcc, s52, v242
	s_nop 1
	v_cndmask_b32_e32 v214, 0, v214, vcc
	ds_write_b32 v39, v214 offset:1056
	v_add_u32_e32 v242, 10, v244
	v_cmp_gt_u32_e32 vcc, s52, v242
	s_nop 1
	v_cndmask_b32_e32 v215, 0, v215, vcc
	ds_write_b32 v39, v215 offset:1320
	v_add_u32_e32 v242, 12, v244
	v_cmp_gt_u32_e32 vcc, s52, v242
	s_nop 1
	v_cndmask_b32_e32 v216, 0, v216, vcc
	ds_write_b32 v39, v216 offset:1584
	v_add_u32_e32 v242, 14, v244
	v_cmp_gt_u32_e32 vcc, s52, v242
	s_nop 1
	v_cndmask_b32_e32 v217, 0, v217, vcc
	ds_write_b32 v39, v217 offset:1848
	v_add_u32_e32 v242, 16, v244
	v_cmp_gt_u32_e32 vcc, s52, v242
	s_nop 1
	v_cndmask_b32_e32 v218, 0, v218, vcc
	ds_write_b32 v39, v218 offset:2112
	v_add_u32_e32 v242, 18, v244
	v_cmp_gt_u32_e32 vcc, s52, v242
	s_nop 1
	v_cndmask_b32_e32 v219, 0, v219, vcc
	ds_write_b32 v39, v219 offset:2376
	v_add_u32_e32 v242, 20, v244
	v_cmp_gt_u32_e32 vcc, s52, v242
	s_nop 1
	v_cndmask_b32_e32 v220, 0, v220, vcc
	ds_write_b32 v39, v220 offset:2640
	v_add_u32_e32 v242, 22, v244
	v_cmp_gt_u32_e32 vcc, s52, v242
	s_nop 1
	v_cndmask_b32_e32 v221, 0, v221, vcc
	ds_write_b32 v39, v221 offset:2904
	v_add_u32_e32 v242, 24, v244
	v_cmp_gt_u32_e32 vcc, s52, v242
	s_nop 1
	v_cndmask_b32_e32 v222, 0, v222, vcc
	ds_write_b32 v39, v222 offset:3168
	v_add_u32_e32 v242, 26, v244
	v_cmp_gt_u32_e32 vcc, s52, v242
	s_nop 1
	v_cndmask_b32_e32 v223, 0, v223, vcc
	ds_write_b32 v39, v223 offset:3432
	v_add_u32_e32 v242, 28, v244
	v_cmp_gt_u32_e32 vcc, s52, v242
	s_nop 1
	v_cndmask_b32_e32 v224, 0, v224, vcc
	ds_write_b32 v39, v224 offset:3696
	v_add_u32_e32 v242, 30, v244
	v_cmp_gt_u32_e32 vcc, s52, v242
	s_nop 1
	v_cndmask_b32_e32 v225, 0, v225, vcc
	ds_write_b32 v39, v225 offset:3960
	v_add_u32_e32 v242, 32, v244
	v_cmp_gt_u32_e32 vcc, s52, v242
	s_nop 1
	v_cndmask_b32_e32 v226, 0, v226, vcc
	ds_write_b32 v39, v226 offset:4224
	v_add_u32_e32 v242, 34, v244
	v_cmp_gt_u32_e32 vcc, s52, v242
	s_nop 1
	v_cndmask_b32_e32 v227, 0, v227, vcc
	ds_write_b32 v39, v227 offset:4488
	v_add_u32_e32 v242, 36, v244
	v_cmp_gt_u32_e32 vcc, s52, v242
	s_nop 1
	v_cndmask_b32_e32 v228, 0, v228, vcc
	ds_write_b32 v39, v228 offset:4752
	v_add_u32_e32 v242, 38, v244
	v_cmp_gt_u32_e32 vcc, s52, v242
	s_nop 1
	v_cndmask_b32_e32 v229, 0, v229, vcc
	ds_write_b32 v39, v229 offset:5016
	v_add_u32_e32 v242, 40, v244
	v_cmp_gt_u32_e32 vcc, s52, v242
	s_nop 1
	v_cndmask_b32_e32 v230, 0, v230, vcc
	ds_write_b32 v39, v230 offset:5280
	v_add_u32_e32 v242, 42, v244
	v_cmp_gt_u32_e32 vcc, s52, v242
	s_nop 1
	v_cndmask_b32_e32 v231, 0, v231, vcc
	ds_write_b32 v39, v231 offset:5544
	v_add_u32_e32 v242, 44, v244
	v_cmp_gt_u32_e32 vcc, s52, v242
	s_nop 1
	v_cndmask_b32_e32 v232, 0, v232, vcc
	ds_write_b32 v39, v232 offset:5808
	v_add_u32_e32 v242, 46, v244
	v_cmp_gt_u32_e32 vcc, s52, v242
	s_nop 1
	v_cndmask_b32_e32 v233, 0, v233, vcc
	ds_write_b32 v39, v233 offset:6072
	v_add_u32_e32 v242, 48, v244
	v_cmp_gt_u32_e32 vcc, s52, v242
	s_nop 1
	v_cndmask_b32_e32 v234, 0, v234, vcc
	ds_write_b32 v39, v234 offset:6336
	v_add_u32_e32 v242, 50, v244
	v_cmp_gt_u32_e32 vcc, s52, v242
	s_nop 1
	v_cndmask_b32_e32 v235, 0, v235, vcc
	ds_write_b32 v39, v235 offset:6600
	v_add_u32_e32 v242, 52, v244
	v_cmp_gt_u32_e32 vcc, s52, v242
	s_nop 1
	v_cndmask_b32_e32 v236, 0, v236, vcc
	ds_write_b32 v39, v236 offset:6864
	v_add_u32_e32 v242, 54, v244
	v_cmp_gt_u32_e32 vcc, s52, v242
	s_nop 1
	v_cndmask_b32_e32 v237, 0, v237, vcc
	ds_write_b32 v39, v237 offset:7128
	v_add_u32_e32 v242, 56, v244
	v_cmp_gt_u32_e32 vcc, s52, v242
	s_nop 1
	v_cndmask_b32_e32 v238, 0, v238, vcc
	ds_write_b32 v39, v238 offset:7392
	v_add_u32_e32 v242, 58, v244
	v_cmp_gt_u32_e32 vcc, s52, v242
	s_nop 1
	v_cndmask_b32_e32 v239, 0, v239, vcc
	ds_write_b32 v39, v239 offset:7656
	v_add_u32_e32 v242, 60, v244
	v_cmp_gt_u32_e32 vcc, s52, v242
	s_nop 1
	v_cndmask_b32_e32 v240, 0, v240, vcc
	ds_write_b32 v39, v240 offset:7920
	v_add_u32_e32 v242, 62, v244
	v_cmp_gt_u32_e32 vcc, s52, v242
	s_nop 1
	v_cndmask_b32_e32 v241, 0, v241, vcc
	ds_write_b32 v39, v241 offset:8184
	s_branch .LBB0_40

.LBB0_41:
	s_andn2_saveexec_b64 s[14:15], s[14:15]
	s_cbranch_execz .LBB0_61
	v_and_b32_e32 v14, 0x3fe0, v51
	v_add_u32_e32 v14, v50, v14
	v_mov_b32_e32 v15, v3
	v_lshlrev_b64 v[30:31], 2, v[14:15]
	v_mul_u32_u24_e32 v14, 0xc00, v11
	v_mul_u32_u24_e32 v16, 0xc00, v16
	v_mov_b32_e32 v17, v3
	v_mul_u32_u24_e32 v18, 0xc00, v18
	v_mov_b32_e32 v19, v3
	v_mul_u32_u24_e32 v20, 0xc00, v20
	v_mov_b32_e32 v21, v3
	v_mul_u32_u24_e32 v22, 0xc00, v22
	v_mov_b32_e32 v23, v3
	v_mul_u32_u24_e32 v24, 0xc00, v24
	v_mov_b32_e32 v25, v3
	v_mul_u32_u24_e32 v26, 0xc00, v26
	v_mov_b32_e32 v27, v3
	v_lshl_add_u64 v[14:15], v[30:31], 0, v[14:15]
	v_lshl_add_u64 v[16:17], v[30:31], 0, v[16:17]
	v_lshl_add_u64 v[18:19], v[30:31], 0, v[18:19]
	v_lshl_add_u64 v[20:21], v[30:31], 0, v[20:21]
	v_lshl_add_u64 v[22:23], v[30:31], 0, v[22:23]
	v_lshl_add_u64 v[24:25], v[30:31], 0, v[24:25]
	v_lshl_add_u64 v[26:27], v[30:31], 0, v[26:27]
	v_mad_u64_u32 v[28:29], s[2:3], v28, s54, v[30:31]
	v_lshl_add_u64 v[14:15], s[50:51], 0, v[14:15]
	v_lshl_add_u64 v[16:17], s[50:51], 0, v[16:17]
	v_lshl_add_u64 v[18:19], s[50:51], 0, v[18:19]
	v_lshl_add_u64 v[20:21], s[50:51], 0, v[20:21]
	v_lshl_add_u64 v[22:23], s[50:51], 0, v[22:23]
	v_lshl_add_u64 v[24:25], s[50:51], 0, v[24:25]
	v_lshl_add_u64 v[26:27], s[50:51], 0, v[26:27]
	v_lshl_add_u64 v[28:29], s[50:51], 0, v[28:29]
	s_mov_b64 s[24:25], 0
	s_mov_b64 s[26:27], s[46:47]
	v_mov_b32_e32 v11, v39
	v_subrev_u32_e32 v245, s50, v28
	global_load_dword v210, v245, s[50:51]
	v_add_u32_e32 v243, 0x1800, v245
	global_load_dword v211, v243, s[50:51]
	v_add_u32_e32 v112, 0x3000, v245
	global_load_dword v212, v112, s[50:51]
	v_add_u32_e32 v243, 0x4800, v245
	global_load_dword v213, v243, s[50:51]
	v_add_u32_e32 v112, 0x6000, v245
	global_load_dword v214, v112, s[50:51]
	v_add_u32_e32 v243, 0x7800, v245
	global_load_dword v215, v243, s[50:51]
	v_add_u32_e32 v112, 0x9000, v245
	global_load_dword v216, v112, s[50:51]
	v_add_u32_e32 v243, 0xa800, v245
	global_load_dword v217, v243, s[50:51]
	v_add_u32_e32 v112, 0xc000, v245
	global_load_dword v218, v112, s[50:51]
	v_add_u32_e32 v243, 0xd800, v245
	global_load_dword v219, v243, s[50:51]
	v_add_u32_e32 v112, 0xf000, v245
	global_load_dword v220, v112, s[50:51]
	v_add_u32_e32 v243, 0x10800, v245
	global_load_dword v221, v243, s[50:51]
	v_add_u32_e32 v112, 0x12000, v245
	global_load_dword v222, v112, s[50:51]
	v_add_u32_e32 v243, 0x13800, v245
	global_load_dword v223, v243, s[50:51]
	v_add_u32_e32 v112, 0x15000, v245
	global_load_dword v224, v112, s[50:51]
	v_add_u32_e32 v243, 0x16800, v245
	global_load_dword v225, v243, s[50:51]
	v_add_u32_e32 v112, 0x18000, v245
	global_load_dword v226, v112, s[50:51]
	v_add_u32_e32 v243, 0x19800, v245
	global_load_dword v227, v243, s[50:51]
	v_add_u32_e32 v112, 0x1b000, v245
	global_load_dword v228, v112, s[50:51]
	v_add_u32_e32 v243, 0x1c800, v245
	global_load_dword v229, v243, s[50:51]
	v_add_u32_e32 v112, 0x1e000, v245
	global_load_dword v230, v112, s[50:51]
	v_add_u32_e32 v243, 0x1f800, v245
	global_load_dword v231, v243, s[50:51]
	v_add_u32_e32 v112, 0x21000, v245
	global_load_dword v232, v112, s[50:51]
	v_add_u32_e32 v243, 0x22800, v245
	global_load_dword v233, v243, s[50:51]
	v_add_u32_e32 v112, 0x24000, v245
	global_load_dword v234, v112, s[50:51]
	v_add_u32_e32 v243, 0x25800, v245
	global_load_dword v235, v243, s[50:51]
	v_add_u32_e32 v112, 0x27000, v245
	global_load_dword v236, v112, s[50:51]
	v_add_u32_e32 v243, 0x28800, v245
	global_load_dword v237, v243, s[50:51]
	v_add_u32_e32 v112, 0x2a000, v245
	global_load_dword v238, v112, s[50:51]
	v_add_u32_e32 v243, 0x2b800, v245
	global_load_dword v239, v243, s[50:51]
	v_add_u32_e32 v112, 0x2d000, v245
	global_load_dword v240, v112, s[50:51]
	v_add_u32_e32 v243, 0x2e800, v245
	global_load_dword v241, v243, s[50:51]
	s_and_b64 vcc, exec, s[10:11]
	s_cbranch_vccz .Lwj2_nogain
	global_load_dword v192, v12, s[46:47]
	global_load_dword v193, v12, s[46:47] offset:8
	global_load_dword v194, v12, s[46:47] offset:16
	global_load_dword v195, v12, s[46:47] offset:24
	global_load_dword v196, v12, s[46:47] offset:32
	global_load_dword v197, v12, s[46:47] offset:40
	global_load_dword v198, v12, s[46:47] offset:48
	global_load_dword v199, v12, s[46:47] offset:56
	global_load_dword v200, v12, s[46:47] offset:64
	global_load_dword v201, v12, s[46:47] offset:72
	global_load_dword v202, v12, s[46:47] offset:80
	global_load_dword v203, v12, s[46:47] offset:88
	global_load_dword v204, v12, s[46:47] offset:96
	global_load_dword v205, v12, s[46:47] offset:104
	global_load_dword v206, v12, s[46:47] offset:112
	global_load_dword v207, v12, s[46:47] offset:120
	global_load_dword v144, v12, s[46:47] offset:128
	global_load_dword v145, v12, s[46:47] offset:136
	global_load_dword v146, v12, s[46:47] offset:144
	global_load_dword v147, v12, s[46:47] offset:152
	global_load_dword v148, v12, s[46:47] offset:160
	global_load_dword v149, v12, s[46:47] offset:168
	global_load_dword v150, v12, s[46:47] offset:176
	global_load_dword v151, v12, s[46:47] offset:184
	global_load_dword v152, v12, s[46:47] offset:192
	global_load_dword v153, v12, s[46:47] offset:200
	global_load_dword v154, v12, s[46:47] offset:208
	global_load_dword v155, v12, s[46:47] offset:216
	global_load_dword v156, v12, s[46:47] offset:224
	global_load_dword v157, v12, s[46:47] offset:232
	global_load_dword v158, v12, s[46:47] offset:240
	global_load_dword v159, v12, s[46:47] offset:248
	s_waitcnt vmcnt(0)
	v_mul_f32_e32 v210, v210, v192
	v_mul_f32_e32 v211, v211, v193
	v_mul_f32_e32 v212, v212, v194
	v_mul_f32_e32 v213, v213, v195
	v_mul_f32_e32 v214, v214, v196
	v_mul_f32_e32 v215, v215, v197
	v_mul_f32_e32 v216, v216, v198
	v_mul_f32_e32 v217, v217, v199
	v_mul_f32_e32 v218, v218, v200
	v_mul_f32_e32 v219, v219, v201
	v_mul_f32_e32 v220, v220, v202
	v_mul_f32_e32 v221, v221, v203
	v_mul_f32_e32 v222, v222, v204
	v_mul_f32_e32 v223, v223, v205
	v_mul_f32_e32 v224, v224, v206
	v_mul_f32_e32 v225, v225, v207
	v_mul_f32_e32 v226, v226, v144
	v_mul_f32_e32 v227, v227, v145
	v_mul_f32_e32 v228, v228, v146
	v_mul_f32_e32 v229, v229, v147
	v_mul_f32_e32 v230, v230, v148
	v_mul_f32_e32 v231, v231, v149
	v_mul_f32_e32 v232, v232, v150
	v_mul_f32_e32 v233, v233, v151
	v_mul_f32_e32 v234, v234, v152
	v_mul_f32_e32 v235, v235, v153
	v_mul_f32_e32 v236, v236, v154
	v_mul_f32_e32 v237, v237, v155
	v_mul_f32_e32 v238, v238, v156
	v_mul_f32_e32 v239, v239, v157
	v_mul_f32_e32 v240, v240, v158
	v_mul_f32_e32 v241, v241, v159
.Lwj2_nogain:
	s_waitcnt vmcnt(0)
	ds_write_b32 v39, v210
	ds_write_b32 v39, v211 offset:264
	ds_write_b32 v39, v212 offset:528
	ds_write_b32 v39, v213 offset:792
	ds_write_b32 v39, v214 offset:1056
	ds_write_b32 v39, v215 offset:1320
	ds_write_b32 v39, v216 offset:1584
	ds_write_b32 v39, v217 offset:1848
	ds_write_b32 v39, v218 offset:2112
	ds_write_b32 v39, v219 offset:2376
	ds_write_b32 v39, v220 offset:2640
	ds_write_b32 v39, v221 offset:2904
	ds_write_b32 v39, v222 offset:3168
	ds_write_b32 v39, v223 offset:3432
	ds_write_b32 v39, v224 offset:3696
	ds_write_b32 v39, v225 offset:3960
	ds_write_b32 v39, v226 offset:4224
	ds_write_b32 v39, v227 offset:4488
	ds_write_b32 v39, v228 offset:4752
	ds_write_b32 v39, v229 offset:5016
	ds_write_b32 v39, v230 offset:5280
	ds_write_b32 v39, v231 offset:5544
	ds_write_b32 v39, v232 offset:5808
	ds_write_b32 v39, v233 offset:6072
	ds_write_b32 v39, v234 offset:6336
	ds_write_b32 v39, v235 offset:6600
	ds_write_b32 v39, v236 offset:6864
	ds_write_b32 v39, v237 offset:7128
	ds_write_b32 v39, v238 offset:7392
	ds_write_b32 v39, v239 offset:7656
	ds_write_b32 v39, v240 offset:7920
	ds_write_b32 v39, v241 offset:8184
	s_branch .LBB0_60

.LBB0_62:
	s_andn2_saveexec_b64 s[2:3], s[12:13]
	s_cbranch_execz .LBB0_11
	v_ashrrev_i32_e32 v2, 31, v54
	v_lshrrev_b32_e32 v2, 28, v2
	v_add_u32_e32 v2, v54, v2
	v_ashrrev_i32_e32 v11, 4, v2
	v_lshlrev_b32_e32 v2, 5, v11
	v_or_b32_e32 v12, v2, v9
	v_ashrrev_i32_e32 v13, 31, v12
	v_lshl_or_b32 v14, v54, 6, v32
	v_lshlrev_b32_e32 v15, 10, v11
	v_cmp_gt_i32_e32 vcc, s55, v12
	v_lshl_add_u64 v[12:13], v[12:13], 2, s[44:45]
	v_sub_u32_e32 v14, v14, v15
	s_mov_b32 s14, 0
	v_mov_b32_e32 v15, v39
	v_subrev_u32_e32 v16, s44, v12
	v_mad_u32_u24 v16, v14, s56, v16
	v_mov_b32_e32 v210, 0
	v_mov_b32_e32 v211, 0
	v_mov_b32_e32 v212, 0
	v_mov_b32_e32 v213, 0
	v_mov_b32_e32 v214, 0
	v_mov_b32_e32 v215, 0
	v_mov_b32_e32 v216, 0
	v_mov_b32_e32 v217, 0
	v_mov_b32_e32 v218, 0
	v_mov_b32_e32 v219, 0
	v_mov_b32_e32 v220, 0
	v_mov_b32_e32 v221, 0
	v_mov_b32_e32 v222, 0
	v_mov_b32_e32 v223, 0
	v_mov_b32_e32 v224, 0
	v_mov_b32_e32 v225, 0
	v_mov_b32_e32 v226, 0
	v_mov_b32_e32 v227, 0
	v_mov_b32_e32 v228, 0
	v_mov_b32_e32 v229, 0
	v_mov_b32_e32 v230, 0
	v_mov_b32_e32 v231, 0
	v_mov_b32_e32 v232, 0
	v_mov_b32_e32 v233, 0
	v_mov_b32_e32 v234, 0
	v_mov_b32_e32 v235, 0
	v_mov_b32_e32 v236, 0
	v_mov_b32_e32 v237, 0
	v_mov_b32_e32 v238, 0
	v_mov_b32_e32 v239, 0
	v_mov_b32_e32 v240, 0
	v_mov_b32_e32 v241, 0
	s_and_saveexec_b64 s[12:13], vcc
	global_load_dword v210, v16, s[44:45]
	v_add_u32_e32 v18, 0x5d00, v16
	global_load_dword v211, v18, s[44:45]
	v_add_u32_e32 v19, 0xba00, v16
	global_load_dword v212, v19, s[44:45]
	v_add_u32_e32 v17, 0x11700, v16
	global_load_dword v213, v17, s[44:45]
	v_add_u32_e32 v18, 0x17400, v16
	global_load_dword v214, v18, s[44:45]
	v_add_u32_e32 v19, 0x1d100, v16
	global_load_dword v215, v19, s[44:45]
	v_add_u32_e32 v17, 0x22e00, v16
	global_load_dword v216, v17, s[44:45]
	v_add_u32_e32 v18, 0x28b00, v16
	global_load_dword v217, v18, s[44:45]
	v_add_u32_e32 v19, 0x2e800, v16
	global_load_dword v218, v19, s[44:45]
	v_add_u32_e32 v17, 0x34500, v16
	global_load_dword v219, v17, s[44:45]
	v_add_u32_e32 v18, 0x3a200, v16
	global_load_dword v220, v18, s[44:45]
	v_add_u32_e32 v19, 0x3ff00, v16
	global_load_dword v221, v19, s[44:45]
	v_add_u32_e32 v17, 0x45c00, v16
	global_load_dword v222, v17, s[44:45]
	v_add_u32_e32 v18, 0x4b900, v16
	global_load_dword v223, v18, s[44:45]
	v_add_u32_e32 v19, 0x51600, v16
	global_load_dword v224, v19, s[44:45]
	v_add_u32_e32 v17, 0x57300, v16
	global_load_dword v225, v17, s[44:45]
	v_add_u32_e32 v18, 0x5d000, v16
	global_load_dword v226, v18, s[44:45]
	v_add_u32_e32 v19, 0x62d00, v16
	global_load_dword v227, v19, s[44:45]
	v_add_u32_e32 v17, 0x68a00, v16
	global_load_dword v228, v17, s[44:45]
	v_add_u32_e32 v18, 0x6e700, v16
	global_load_dword v229, v18, s[44:45]
	v_add_u32_e32 v19, 0x74400, v16
	global_load_dword v230, v19, s[44:45]
	v_add_u32_e32 v17, 0x7a100, v16
	global_load_dword v231, v17, s[44:45]
	v_add_u32_e32 v18, 0x7fe00, v16
	global_load_dword v232, v18, s[44:45]
	v_add_u32_e32 v19, 0x85b00, v16
	global_load_dword v233, v19, s[44:45]
	v_add_u32_e32 v17, 0x8b800, v16
	global_load_dword v234, v17, s[44:45]
	v_add_u32_e32 v18, 0x91500, v16
	global_load_dword v235, v18, s[44:45]
	v_add_u32_e32 v19, 0x97200, v16
	global_load_dword v236, v19, s[44:45]
	v_add_u32_e32 v17, 0x9cf00, v16
	global_load_dword v237, v17, s[44:45]
	v_add_u32_e32 v18, 0xa2c00, v16
	global_load_dword v238, v18, s[44:45]
	v_add_u32_e32 v19, 0xa8900, v16
	global_load_dword v239, v19, s[44:45]
	v_add_u32_e32 v17, 0xae600, v16
	global_load_dword v240, v17, s[44:45]
	v_add_u32_e32 v18, 0xb4300, v16
	global_load_dword v241, v18, s[44:45]
	s_or_b64 exec, exec, s[12:13]
	s_waitcnt vmcnt(0)
	ds_write_b32 v15, v210
	ds_write_b32 v15, v211 offset:264
	ds_write_b32 v15, v212 offset:528
	ds_write_b32 v15, v213 offset:792
	ds_write_b32 v15, v214 offset:1056
	ds_write_b32 v15, v215 offset:1320
	ds_write_b32 v15, v216 offset:1584
	ds_write_b32 v15, v217 offset:1848
	ds_write_b32 v15, v218 offset:2112
	ds_write_b32 v15, v219 offset:2376
	ds_write_b32 v15, v220 offset:2640
	ds_write_b32 v15, v221 offset:2904
	ds_write_b32 v15, v222 offset:3168
	ds_write_b32 v15, v223 offset:3432
	ds_write_b32 v15, v224 offset:3696
	ds_write_b32 v15, v225 offset:3960
	ds_write_b32 v15, v226 offset:4224
	ds_write_b32 v15, v227 offset:4488
	ds_write_b32 v15, v228 offset:4752
	ds_write_b32 v15, v229 offset:5016
	ds_write_b32 v15, v230 offset:5280
	ds_write_b32 v15, v231 offset:5544
	ds_write_b32 v15, v232 offset:5808
	ds_write_b32 v15, v233 offset:6072
	ds_write_b32 v15, v234 offset:6336
	ds_write_b32 v15, v235 offset:6600
	ds_write_b32 v15, v236 offset:6864
	ds_write_b32 v15, v237 offset:7128
	ds_write_b32 v15, v238 offset:7392
	ds_write_b32 v15, v239 offset:7656
	ds_write_b32 v15, v240 offset:7920
	ds_write_b32 v15, v241 offset:8184
	s_branch .LBB0_10
